# phase 0 W_in transpose: four row loads and gain loads of a tile issued together instead of one round trip each
# speedup vs baseline: 1.0095x; 1.0012x over previous
.LBB0_17:
	s_waitcnt vmcnt(0)
	v_pk_mul_f32 v[2:3], v[48:49], v[58:59] op_sel_hi:[1,0]
	ds_write2_b32 v28, v2, v3 offset1:1
	v_pk_mul_f32 v[2:3], v[50:51], v[58:59] op_sel_hi:[1,0]
	v_add_u32_e32 v7, 0x800, v24
	ds_write2_b32 v28, v2, v3 offset0:2 offset1:3
	s_waitcnt lgkmcnt(0)
	s_barrier
	ds_read2_b32 v[2:3], v24 offset1:65
	ds_read2_b32 v[4:5], v7 offset0:8 offset1:73
	ds_read2_b32 v[8:9], v24 offset0:130 offset1:195
	v_add_u32_e32 v18, 0xc00, v24
	s_sub_i32 s7, 0, s7
	s_add_i32 s7, s7, s10
	s_waitcnt lgkmcnt(1)
	v_cvt_pk_bf16_f32 v6, v4, v5
	ds_read2_b32 v[4:5], v7 offset0:138 offset1:203
	v_add_u32_e32 v7, 0x400, v24
	v_cvt_pk_bf16_f32 v2, v2, v3
	s_waitcnt lgkmcnt(1)
	v_cvt_pk_bf16_f32 v3, v8, v9
	ds_read2_b32 v[8:9], v7 offset0:4 offset1:69
	ds_read2_b32 v[14:15], v18 offset0:12 offset1:77
	ds_read2_b32 v[16:17], v7 offset0:134 offset1:199
	ds_read2_b32 v[18:19], v18 offset0:142 offset1:207
	s_waitcnt lgkmcnt(4)
	v_cvt_pk_bf16_f32 v7, v4, v5
	s_add_i32 s10, s10, s11
	s_waitcnt lgkmcnt(3)
	v_cvt_pk_bf16_f32 v4, v8, v9
	s_waitcnt lgkmcnt(2)
	v_cvt_pk_bf16_f32 v8, v14, v15
	v_add_u32_e32 v14, s7, v23
	v_ashrrev_i32_e32 v15, 31, v14
	v_lshlrev_b64 v[14:15], 11, v[14:15]
	v_lshl_add_u64 v[14:15], s[8:9], 0, v[14:15]
	s_ashr_i32 s7, s6, 31
	v_lshl_add_u64 v[14:15], s[6:7], 1, v[14:15]
	v_readlane_b32 s6, v254, 12
	s_add_i32 s12, s12, s6
	s_waitcnt lgkmcnt(1)
	v_cvt_pk_bf16_f32 v5, v16, v17
	s_waitcnt lgkmcnt(0)
	v_cvt_pk_bf16_f32 v9, v18, v19
	v_lshl_add_u64 v[14:15], v[14:15], 0, v[10:11]
	s_cmpk_lt_i32 s12, 0x800
	global_store_dwordx4 v[14:15], v[2:5], off
	v_readlane_b32 s7, v254, 13
	global_store_dwordx4 v[14:15], v[6:9], off offset:16
	s_cbranch_scc0 .LBB0_26
.LBB0_18:
	s_ashr_i32 s6, s12, 31
	s_lshr_b32 s6, s6, 25
	s_add_i32 s6, s12, s6
	s_ashr_i32 s7, s6, 7
	s_lshl_b32 s6, s7, 6
	s_lshl_b32 s7, s7, 13
	s_sub_i32 s14, s10, s7
	v_add_u32_e32 v18, s6, v21
	s_ashr_i32 s15, s14, 31
	v_ashrrev_i32_e32 v19, 31, v18
	v_lshl_add_u64 v[16:17], s[14:15], 2, v[12:13]
	v_lshlrev_b64 v[2:3], 15, v[18:19]
	v_lshl_add_u64 v[2:3], v[16:17], 0, v[2:3]
	v_lshl_add_u64 v[14:15], v[18:19], 2, s[4:5]
	s_mov_b32 s14, 0x80000
	s_mov_b32 s15, 0
	v_lshl_add_u64 v[30:31], v[2:3], 0, s[14:15]
	v_lshl_add_u64 v[32:33], v[30:31], 0, s[14:15]
	v_lshl_add_u64 v[34:35], v[32:33], 0, s[14:15]
	v_mov_b32_e32 v52, 1.0
	v_mov_b32_e32 v54, 1.0
	v_mov_b32_e32 v56, 1.0
	v_mov_b32_e32 v58, 1.0
	s_and_b64 vcc, exec, s[2:3]
	s_barrier
	s_cbranch_vccnz .Lp0_nogain
	global_load_dword v52, v[14:15], off
	global_load_dword v54, v[14:15], off offset:64
	global_load_dword v56, v[14:15], off offset:128
	global_load_dword v58, v[14:15], off offset:192
.Lp0_nogain:
	global_load_dwordx4 v[36:39], v[2:3], off
	global_load_dwordx4 v[40:43], v[30:31], off
	global_load_dwordx4 v[44:47], v[32:33], off
	global_load_dwordx4 v[48:51], v[34:35], off
	s_waitcnt vmcnt(3)
	v_pk_mul_f32 v[2:3], v[36:37], v[52:53] op_sel_hi:[1,0]
	ds_write2_b32 v25, v2, v3 offset1:1
	v_pk_mul_f32 v[2:3], v[38:39], v[52:53] op_sel_hi:[1,0]
	ds_write2_b32 v25, v2, v3 offset0:2 offset1:3
	s_waitcnt vmcnt(2)
	v_pk_mul_f32 v[2:3], v[40:41], v[54:55] op_sel_hi:[1,0]
	ds_write2_b32 v26, v2, v3 offset1:1
	v_pk_mul_f32 v[2:3], v[42:43], v[54:55] op_sel_hi:[1,0]
	ds_write2_b32 v26, v2, v3 offset0:2 offset1:3
	s_waitcnt vmcnt(1)
	v_pk_mul_f32 v[2:3], v[44:45], v[56:57] op_sel_hi:[1,0]
	ds_write2_b32 v27, v2, v3 offset1:1
	v_pk_mul_f32 v[2:3], v[46:47], v[56:57] op_sel_hi:[1,0]
	ds_write2_b32 v27, v2, v3 offset0:2 offset1:3
	s_branch .LBB0_17
